# EpiOutMod phase A as well: xin loads of the next row group issued before the current one is consumed
# baseline (speedup 1.0000x reference)
;     __device__ __forceinline__ void fused(f32x4 (&acc)[2][2][4][2], const Unit& u, int wr, int wc, int fr, int fq, PG8_LAS unsigned char* lds, int wid, int lane) const {
;     ...
;         for (int ai = 0; ai < 2; ++ai)
; #pragma unroll
;             for (int m = 0; m < 4; ++m) { const size_t ro = (size_t)(row0 + ai * HALF + m * 16) * 1024 + col0; float s = 0.f;
; #pragma unroll
;                 for (int bj = 0; bj < 2; ++bj)
; #pragma unroll
;                     for (int n = 0; n < 2; ++n) { const f32x4 xi = __builtin_nontemporal_load((const f32x4*)(xin + ro + bj * HALF + 16 * n));
;                         const f32x4 v = xi + gt[bj][n] * acc[ai][bj][m][n]; acc[ai][bj][m][n] = v;
;                         *(f32x4*)(xout + ro + bj * HALF + 16 * n) = v;
;                         s += (v[0] * v[0] + v[1] * v[1]) + (v[2] * v[2] + v[3] * v[3]); }
;                 s += __shfl_xor(s, 16); s += __shfl_xor(s, 32);
;                 if (fq == 0) P[(ai * HALF + wr * 64 + m * 16 + fr) * 4 + wc] = s; }
.LBB0_615:
	s_lshl_b32 s30, s20, 8
	s_lshl_b32 s27, s21, 5
	s_add_i32 s36, s30, s5
	s_lshl_b32 s30, s26, 8
	s_or_b32 s27, s30, s27
	v_lshrrev_b32_e32 v132, 2, v191
	v_and_or_b32 v180, v132, 12, s27
	s_ashr_i32 s27, s20, 3
	s_mul_i32 s34, s27, 0x3000
	v_readlane_b32 s30, v253, 48
	s_mul_hi_i32 s33, s27, 0x3000
	v_readlane_b32 s31, v253, 49
	s_add_u32 s30, s30, s34
	s_addc_u32 s31, s31, s33
	v_ashrrev_i32_e32 v181, 31, v180
	v_lshl_add_u64 v[132:133], v[180:181], 2, s[30:31]
	s_movk_i32 s27, 0x2000
	v_add_co_u32_e32 v134, vcc, s27, v132
	v_or_b32_e32 v182, s36, v210
	s_nop 0
	v_addc_co_u32_e32 v135, vcc, 0, v133, vcc
	v_ashrrev_i32_e32 v183, 31, v182
	s_waitcnt vmcnt(0)
	s_barrier
	global_load_dwordx4 v[140:143], v[134:135], off
	v_lshlrev_b64 v[134:135], 10, v[182:183]
	v_lshl_add_u64 v[134:135], v[134:135], 0, v[180:181]
	v_lshlrev_b64 v[154:155], 2, v[134:135]
	v_lshl_add_u64 v[156:157], s[18:19], 0, v[154:155]
	v_mov_b32_e32 v194, v156
	v_mov_b32_e32 v195, v157
	global_load_dwordx4 v[212:215], v[156:157], off nt
	global_load_dwordx4 v[216:219], v[156:157], off offset:64 nt
	global_load_dwordx4 v[220:223], v[156:157], off offset:512 nt
	global_load_dwordx4 v[242:245], v[156:157], off offset:576 nt
	s_mov_b64 s[30:31], 0x2000
	v_lshl_add_u64 v[132:133], v[132:133], 0, s[30:31]
	v_lshl_add_u64 v[158:159], s[78:79], 0, v[154:155]
	global_load_dwordx4 v[144:147], v[132:133], off offset:64
	global_load_dwordx4 v[136:139], v[132:133], off offset:512
	s_nop 0
	global_load_dwordx4 v[132:135], v[132:133], off offset:576
	s_lshl_b32 s21, s21, 2
	v_and_b32_e32 v149, 63, v191
	s_add_i32 s21, s21, 0
	v_lshl_add_u32 v148, v148, 4, s21
	s_mov_b64 s[98:99], 0x10000
	v_lshl_add_u64 v[178:179], v[194:195], 0, s[98:99]
	global_load_dwordx4 v[162:165], v[178:179], off nt
	global_load_dwordx4 v[166:169], v[178:179], off offset:64 nt
	global_load_dwordx4 v[170:173], v[178:179], off offset:512 nt
	global_load_dwordx4 v[174:177], v[178:179], off offset:576 nt
	s_waitcnt vmcnt(4)
	v_pk_fma_f32 v[110:111], v[110:111], v[142:143], v[214:215]
	v_pk_fma_f32 v[108:109], v[108:109], v[140:141], v[212:213]
	global_store_dwordx4 v[158:159], v[108:111], off
	v_mul_f32_e32 v160, v111, v111
	v_fmac_f32_e32 v160, v110, v110
	s_waitcnt vmcnt(5)
	v_pk_fma_f32 v[122:123], v[122:123], v[146:147], v[218:219]
	v_pk_fma_f32 v[120:121], v[120:121], v[144:145], v[216:217]
	global_store_dwordx4 v[158:159], v[120:123], off offset:64
	v_mul_f32_e32 v161, v123, v123
	v_fmac_f32_e32 v161, v122, v122
	s_waitcnt vmcnt(6)
	v_pk_fma_f32 v[114:115], v[114:115], v[138:139], v[222:223]
	v_pk_fma_f32 v[112:113], v[112:113], v[136:137], v[220:221]
	global_store_dwordx4 v[158:159], v[112:115], off offset:512
	v_mul_f32_e32 v157, v109, v109
	v_fmac_f32_e32 v157, v108, v108
	v_add_f32_e32 v157, v157, v160
	v_mul_f32_e32 v160, v121, v121
	v_fmac_f32_e32 v160, v120, v120
	v_add_f32_e32 v160, v160, v161
	v_and_b32_e32 v151, 64, v224
	v_add_f32_e32 v157, v157, v160
	v_mul_f32_e32 v160, v113, v113
	v_mul_f32_e32 v161, v115, v115
	v_xor_b32_e32 v150, 16, v224
	v_add_u32_e32 v151, 64, v151
	v_fmac_f32_e32 v160, v112, v112
	v_fmac_f32_e32 v161, v114, v114
	v_cmp_lt_i32_e32 vcc, v150, v151
	v_add_f32_e32 v160, v160, v161
	v_add_f32_e32 v157, v157, v160
	v_cndmask_b32_e32 v150, v224, v150, vcc
	v_lshlrev_b32_e32 v150, 2, v150
	v_xor_b32_e32 v156, 32, v224
	v_cmp_lt_i32_e32 vcc, v156, v151
	s_waitcnt vmcnt(7)
	v_pk_fma_f32 v[130:131], v[130:131], v[134:135], v[244:245]
	v_pk_fma_f32 v[128:129], v[128:129], v[132:133], v[242:243]
	v_mul_f32_e32 v153, v131, v131
	v_mul_f32_e32 v152, v129, v129
	v_fmac_f32_e32 v152, v128, v128
	v_fmac_f32_e32 v153, v130, v130
	v_add_f32_e32 v152, v152, v153
	v_add_f32_e32 v152, v157, v152
	ds_bpermute_b32 v153, v150, v152
	v_cndmask_b32_e32 v151, v224, v156, vcc
	v_lshlrev_b32_e32 v151, 2, v151
	v_cmp_gt_u32_e32 vcc, 16, v149
	global_store_dwordx4 v[158:159], v[128:131], off offset:576
	s_waitcnt lgkmcnt(0)
	v_add_f32_e32 v152, v152, v153
	ds_bpermute_b32 v153, v151, v152
	s_and_saveexec_b64 s[30:31], vcc
	s_cbranch_execz .LBB0_617
	s_waitcnt lgkmcnt(0)
	v_add_f32_e32 v152, v152, v153
	ds_write_b32 v148, v152
.LBB0_617:
	s_or_b64 exec, exec, s[30:31]
	v_or_b32_e32 v184, 16, v182
	v_ashrrev_i32_e32 v185, 31, v184
	s_waitcnt lgkmcnt(0)
	v_lshlrev_b64 v[152:153], 10, v[184:185]
	v_lshl_add_u64 v[152:153], v[152:153], 0, v[180:181]
	v_lshlrev_b64 v[156:157], 2, v[152:153]
	v_lshl_add_u64 v[158:159], s[18:19], 0, v[156:157]
	s_mov_b64 s[98:99], 0x20000
	v_lshl_add_u64 v[178:179], v[194:195], 0, s[98:99]
	global_load_dwordx4 v[212:215], v[178:179], off nt
	global_load_dwordx4 v[216:219], v[178:179], off offset:64 nt
	global_load_dwordx4 v[220:223], v[178:179], off offset:512 nt
	global_load_dwordx4 v[242:245], v[178:179], off offset:576 nt
	v_lshl_add_u64 v[156:157], s[78:79], 0, v[156:157]
	s_waitcnt vmcnt(11)
	v_pk_fma_f32 v[126:127], v[126:127], v[142:143], v[164:165]
	v_pk_fma_f32 v[124:125], v[124:125], v[140:141], v[162:163]
	global_store_dwordx4 v[156:157], v[124:127], off
	s_waitcnt vmcnt(11)
	v_pk_fma_f32 v[118:119], v[118:119], v[146:147], v[168:169]
	v_pk_fma_f32 v[116:117], v[116:117], v[144:145], v[166:167]
	global_store_dwordx4 v[156:157], v[116:119], off offset:64
	v_mul_f32_e32 v160, v119, v119
	v_fmac_f32_e32 v160, v118, v118
	s_waitcnt vmcnt(11)
	v_pk_fma_f32 v[106:107], v[106:107], v[138:139], v[172:173]
	v_pk_fma_f32 v[104:105], v[104:105], v[136:137], v[170:171]
	global_store_dwordx4 v[156:157], v[104:107], off offset:512
	v_mul_f32_e32 v158, v125, v125
	v_mul_f32_e32 v159, v127, v127
	v_fmac_f32_e32 v158, v124, v124
	v_fmac_f32_e32 v159, v126, v126
	v_add_f32_e32 v158, v158, v159
	v_mul_f32_e32 v159, v117, v117
	v_fmac_f32_e32 v159, v116, v116
	v_add_f32_e32 v159, v159, v160
	v_add_f32_e32 v158, v158, v159
	v_mul_f32_e32 v159, v105, v105
	v_mul_f32_e32 v160, v107, v107
	v_fmac_f32_e32 v159, v104, v104
	v_fmac_f32_e32 v160, v106, v106
	v_add_f32_e32 v159, v159, v160
	v_add_f32_e32 v158, v158, v159
	s_waitcnt vmcnt(11)
	v_pk_fma_f32 v[102:103], v[102:103], v[134:135], v[176:177]
	v_pk_fma_f32 v[100:101], v[100:101], v[132:133], v[174:175]
	v_mul_f32_e32 v153, v103, v103
	v_mul_f32_e32 v152, v101, v101
	v_fmac_f32_e32 v152, v100, v100
	v_fmac_f32_e32 v153, v102, v102
	v_add_f32_e32 v152, v152, v153
	v_add_f32_e32 v152, v158, v152
	ds_bpermute_b32 v153, v150, v152
	global_store_dwordx4 v[156:157], v[100:103], off offset:576
	s_waitcnt lgkmcnt(0)
	v_add_f32_e32 v152, v152, v153
	ds_bpermute_b32 v153, v151, v152
	s_and_saveexec_b64 s[30:31], vcc
	s_cbranch_execz .LBB0_619
	s_waitcnt lgkmcnt(0)
	v_add_f32_e32 v152, v152, v153
	ds_write_b32 v148, v152 offset:256
;     __device__ __forceinline__ void fused(f32x4 (&acc)[2][2][4][2], const Unit& u, int wr, int wc, int fr, int fq, PG8_LAS unsigned char* lds, int wid, int lane) const {
;     ...
;             for (int m = 0; m < 4; ++m) { const size_t ro = (size_t)(row0 + ai * HALF + m * 16) * 1024 + col0; float s = 0.f;
; #pragma unroll
;                 for (int bj = 0; bj < 2; ++bj)
; #pragma unroll
;                     for (int n = 0; n < 2; ++n) { const f32x4 xi = __builtin_nontemporal_load((const f32x4*)(xin + ro + bj * HALF + 16 * n));
;                         const f32x4 v = xi + gt[bj][n] * acc[ai][bj][m][n]; acc[ai][bj][m][n] = v;
;                         *(f32x4*)(xout + ro + bj * HALF + 16 * n) = v;
;                         s += (v[0] * v[0] + v[1] * v[1]) + (v[2] * v[2] + v[3] * v[3]); }
;                 s += __shfl_xor(s, 16); s += __shfl_xor(s, 32);
;                 if (fq == 0) P[(ai * HALF + wr * 64 + m * 16 + fr) * 4 + wc] = s; }
.LBB0_619:
	s_or_b64 exec, exec, s[30:31]
	v_or_b32_e32 v186, 32, v182
	v_ashrrev_i32_e32 v187, 31, v186
	s_waitcnt lgkmcnt(0)
	v_lshlrev_b64 v[152:153], 10, v[186:187]
	v_lshl_add_u64 v[152:153], v[152:153], 0, v[180:181]
	v_lshlrev_b64 v[156:157], 2, v[152:153]
	v_lshl_add_u64 v[158:159], s[18:19], 0, v[156:157]
	s_mov_b64 s[98:99], 0x30000
	v_lshl_add_u64 v[178:179], v[194:195], 0, s[98:99]
	global_load_dwordx4 v[162:165], v[178:179], off nt
	global_load_dwordx4 v[166:169], v[178:179], off offset:64 nt
	global_load_dwordx4 v[170:173], v[178:179], off offset:512 nt
	global_load_dwordx4 v[174:177], v[178:179], off offset:576 nt
	v_lshl_add_u64 v[156:157], s[78:79], 0, v[156:157]
	s_waitcnt vmcnt(11)
	v_pk_fma_f32 v[98:99], v[98:99], v[142:143], v[214:215]
	v_pk_fma_f32 v[96:97], v[96:97], v[140:141], v[212:213]
	global_store_dwordx4 v[156:157], v[96:99], off
	s_waitcnt vmcnt(11)
	v_pk_fma_f32 v[94:95], v[94:95], v[146:147], v[218:219]
	v_pk_fma_f32 v[92:93], v[92:93], v[144:145], v[216:217]
	global_store_dwordx4 v[156:157], v[92:95], off offset:64
	v_mul_f32_e32 v160, v95, v95
	v_fmac_f32_e32 v160, v94, v94
	s_waitcnt vmcnt(11)
	v_pk_fma_f32 v[90:91], v[90:91], v[138:139], v[222:223]
	v_pk_fma_f32 v[88:89], v[88:89], v[136:137], v[220:221]
	global_store_dwordx4 v[156:157], v[88:91], off offset:512
	v_mul_f32_e32 v158, v97, v97
	v_mul_f32_e32 v159, v99, v99
	v_fmac_f32_e32 v158, v96, v96
	v_fmac_f32_e32 v159, v98, v98
	v_add_f32_e32 v158, v158, v159
	v_mul_f32_e32 v159, v93, v93
	v_fmac_f32_e32 v159, v92, v92
	v_add_f32_e32 v159, v159, v160
	v_add_f32_e32 v158, v158, v159
	v_mul_f32_e32 v159, v89, v89
	v_mul_f32_e32 v160, v91, v91
	v_fmac_f32_e32 v159, v88, v88
	v_fmac_f32_e32 v160, v90, v90
	v_add_f32_e32 v159, v159, v160
	v_add_f32_e32 v158, v158, v159
	s_waitcnt vmcnt(11)
	v_pk_fma_f32 v[86:87], v[86:87], v[134:135], v[244:245]
	v_pk_fma_f32 v[84:85], v[84:85], v[132:133], v[242:243]
	v_mul_f32_e32 v153, v87, v87
	v_mul_f32_e32 v152, v85, v85
	v_fmac_f32_e32 v152, v84, v84
	v_fmac_f32_e32 v153, v86, v86
	v_add_f32_e32 v152, v152, v153
	v_add_f32_e32 v152, v158, v152
	ds_bpermute_b32 v153, v150, v152
	global_store_dwordx4 v[156:157], v[84:87], off offset:576
	s_waitcnt lgkmcnt(0)
	v_add_f32_e32 v152, v152, v153
	ds_bpermute_b32 v153, v151, v152
	s_and_saveexec_b64 s[30:31], vcc
	s_cbranch_execz .LBB0_621
	s_waitcnt lgkmcnt(0)
	v_add_f32_e32 v152, v152, v153
	ds_write_b32 v148, v152 offset:512
.LBB0_621:
	s_or_b64 exec, exec, s[30:31]
	v_or_b32_e32 v198, 48, v182
	v_ashrrev_i32_e32 v199, 31, v198
	s_waitcnt lgkmcnt(0)
	v_lshlrev_b64 v[152:153], 10, v[198:199]
	v_lshl_add_u64 v[152:153], v[152:153], 0, v[180:181]
	v_lshlrev_b64 v[156:157], 2, v[152:153]
	v_lshl_add_u64 v[158:159], s[18:19], 0, v[156:157]
	s_mov_b64 s[98:99], 0x80000
	v_lshl_add_u64 v[178:179], v[194:195], 0, s[98:99]
	global_load_dwordx4 v[212:215], v[178:179], off nt
	global_load_dwordx4 v[216:219], v[178:179], off offset:64 nt
	global_load_dwordx4 v[220:223], v[178:179], off offset:512 nt
	global_load_dwordx4 v[242:245], v[178:179], off offset:576 nt
	v_lshl_add_u64 v[156:157], s[78:79], 0, v[156:157]
	s_waitcnt vmcnt(11)
	v_pk_fma_f32 v[82:83], v[82:83], v[142:143], v[164:165]
	v_pk_fma_f32 v[80:81], v[80:81], v[140:141], v[162:163]
	global_store_dwordx4 v[156:157], v[80:83], off
	s_waitcnt vmcnt(11)
	v_pk_fma_f32 v[78:79], v[78:79], v[146:147], v[168:169]
	v_pk_fma_f32 v[76:77], v[76:77], v[144:145], v[166:167]
	global_store_dwordx4 v[156:157], v[76:79], off offset:64
	v_mul_f32_e32 v160, v79, v79
	v_fmac_f32_e32 v160, v78, v78
	s_waitcnt vmcnt(11)
	v_pk_fma_f32 v[74:75], v[74:75], v[138:139], v[172:173]
	v_pk_fma_f32 v[72:73], v[72:73], v[136:137], v[170:171]
	global_store_dwordx4 v[156:157], v[72:75], off offset:512
	v_mul_f32_e32 v158, v81, v81
	v_mul_f32_e32 v159, v83, v83
	v_fmac_f32_e32 v158, v80, v80
	v_fmac_f32_e32 v159, v82, v82
	v_add_f32_e32 v158, v158, v159
	v_mul_f32_e32 v159, v77, v77
	v_fmac_f32_e32 v159, v76, v76
	v_add_f32_e32 v159, v159, v160
	v_add_f32_e32 v158, v158, v159
	v_mul_f32_e32 v159, v73, v73
	v_mul_f32_e32 v160, v75, v75
	v_fmac_f32_e32 v159, v72, v72
	v_fmac_f32_e32 v160, v74, v74
	v_add_f32_e32 v159, v159, v160
	v_add_f32_e32 v158, v158, v159
	s_waitcnt vmcnt(11)
	v_pk_fma_f32 v[70:71], v[70:71], v[134:135], v[176:177]
	v_pk_fma_f32 v[68:69], v[68:69], v[132:133], v[174:175]
	v_mul_f32_e32 v153, v71, v71
	v_mul_f32_e32 v152, v69, v69
	v_fmac_f32_e32 v152, v68, v68
	v_fmac_f32_e32 v153, v70, v70
	v_add_f32_e32 v152, v152, v153
	v_add_f32_e32 v152, v158, v152
	ds_bpermute_b32 v153, v150, v152
	global_store_dwordx4 v[156:157], v[68:71], off offset:576
	s_waitcnt lgkmcnt(0)
	v_add_f32_e32 v152, v152, v153
	ds_bpermute_b32 v153, v151, v152
	s_and_saveexec_b64 s[30:31], vcc
	s_cbranch_execz .LBB0_623
	s_waitcnt lgkmcnt(0)
	v_add_f32_e32 v152, v152, v153
	ds_write_b32 v148, v152 offset:768
;     __device__ __forceinline__ void fused(f32x4 (&acc)[2][2][4][2], const Unit& u, int wr, int wc, int fr, int fq, PG8_LAS unsigned char* lds, int wid, int lane) const {
;     ...
;             for (int m = 0; m < 4; ++m) { const size_t ro = (size_t)(row0 + ai * HALF + m * 16) * 1024 + col0; float s = 0.f;
; #pragma unroll
;                 for (int bj = 0; bj < 2; ++bj)
; #pragma unroll
;                     for (int n = 0; n < 2; ++n) { const f32x4 xi = __builtin_nontemporal_load((const f32x4*)(xin + ro + bj * HALF + 16 * n));
;                         const f32x4 v = xi + gt[bj][n] * acc[ai][bj][m][n]; acc[ai][bj][m][n] = v;
;                         *(f32x4*)(xout + ro + bj * HALF + 16 * n) = v;
;                         s += (v[0] * v[0] + v[1] * v[1]) + (v[2] * v[2] + v[3] * v[3]); }
;                 s += __shfl_xor(s, 16); s += __shfl_xor(s, 32);
;                 if (fq == 0) P[(ai * HALF + wr * 64 + m * 16 + fr) * 4 + wc] = s; }
.LBB0_623:
	s_or_b64 exec, exec, s[30:31]
	v_add_u32_e32 v200, 0x80, v182
	v_ashrrev_i32_e32 v201, 31, v200
	s_waitcnt lgkmcnt(0)
	v_lshlrev_b64 v[152:153], 10, v[200:201]
	v_lshl_add_u64 v[152:153], v[152:153], 0, v[180:181]
	v_lshlrev_b64 v[156:157], 2, v[152:153]
	v_lshl_add_u64 v[158:159], s[18:19], 0, v[156:157]
	s_mov_b64 s[98:99], 0x90000
	v_lshl_add_u64 v[178:179], v[194:195], 0, s[98:99]
	global_load_dwordx4 v[162:165], v[178:179], off nt
	global_load_dwordx4 v[166:169], v[178:179], off offset:64 nt
	global_load_dwordx4 v[170:173], v[178:179], off offset:512 nt
	global_load_dwordx4 v[174:177], v[178:179], off offset:576 nt
	v_lshl_add_u64 v[156:157], s[78:79], 0, v[156:157]
	s_waitcnt vmcnt(11)
	v_pk_fma_f32 v[66:67], v[66:67], v[142:143], v[214:215]
	v_pk_fma_f32 v[64:65], v[64:65], v[140:141], v[212:213]
	global_store_dwordx4 v[156:157], v[64:67], off
	s_waitcnt vmcnt(11)
	v_pk_fma_f32 v[62:63], v[62:63], v[146:147], v[218:219]
	v_pk_fma_f32 v[60:61], v[60:61], v[144:145], v[216:217]
	global_store_dwordx4 v[156:157], v[60:63], off offset:64
	v_mul_f32_e32 v160, v63, v63
	v_fmac_f32_e32 v160, v62, v62
	s_waitcnt vmcnt(11)
	v_pk_fma_f32 v[58:59], v[58:59], v[138:139], v[222:223]
	v_pk_fma_f32 v[56:57], v[56:57], v[136:137], v[220:221]
	global_store_dwordx4 v[156:157], v[56:59], off offset:512
	v_mul_f32_e32 v158, v65, v65
	v_mul_f32_e32 v159, v67, v67
	v_fmac_f32_e32 v158, v64, v64
	v_fmac_f32_e32 v159, v66, v66
	v_add_f32_e32 v158, v158, v159
	v_mul_f32_e32 v159, v61, v61
	v_fmac_f32_e32 v159, v60, v60
	v_add_f32_e32 v159, v159, v160
	v_add_f32_e32 v158, v158, v159
	v_mul_f32_e32 v159, v57, v57
	v_mul_f32_e32 v160, v59, v59
	v_fmac_f32_e32 v159, v56, v56
	v_fmac_f32_e32 v160, v58, v58
	v_add_f32_e32 v159, v159, v160
	v_add_f32_e32 v158, v158, v159
	s_waitcnt vmcnt(11)
	v_pk_fma_f32 v[54:55], v[54:55], v[134:135], v[244:245]
	v_pk_fma_f32 v[52:53], v[52:53], v[132:133], v[242:243]
	v_mul_f32_e32 v153, v55, v55
	v_mul_f32_e32 v152, v53, v53
	v_fmac_f32_e32 v152, v52, v52
	v_fmac_f32_e32 v153, v54, v54
	v_add_f32_e32 v152, v152, v153
	v_add_f32_e32 v152, v158, v152
	ds_bpermute_b32 v153, v150, v152
	global_store_dwordx4 v[156:157], v[52:55], off offset:576
	s_waitcnt lgkmcnt(0)
	v_add_f32_e32 v152, v152, v153
	ds_bpermute_b32 v153, v151, v152
	s_and_saveexec_b64 s[30:31], vcc
	s_cbranch_execz .LBB0_625
	s_waitcnt lgkmcnt(0)
	v_add_f32_e32 v152, v152, v153
	ds_write_b32 v148, v152 offset:2048
.LBB0_625:
	s_or_b64 exec, exec, s[30:31]
	v_add_u32_e32 v202, 0x90, v182
	v_ashrrev_i32_e32 v203, 31, v202
	s_waitcnt lgkmcnt(0)
	v_lshlrev_b64 v[152:153], 10, v[202:203]
	v_lshl_add_u64 v[152:153], v[152:153], 0, v[180:181]
	v_lshlrev_b64 v[156:157], 2, v[152:153]
	v_lshl_add_u64 v[158:159], s[18:19], 0, v[156:157]
	s_mov_b64 s[98:99], 0xa0000
	v_lshl_add_u64 v[178:179], v[194:195], 0, s[98:99]
	global_load_dwordx4 v[212:215], v[178:179], off nt
	global_load_dwordx4 v[216:219], v[178:179], off offset:64 nt
	global_load_dwordx4 v[220:223], v[178:179], off offset:512 nt
	global_load_dwordx4 v[242:245], v[178:179], off offset:576 nt
	v_lshl_add_u64 v[156:157], s[78:79], 0, v[156:157]
	s_waitcnt vmcnt(11)
	v_pk_fma_f32 v[50:51], v[50:51], v[142:143], v[164:165]
	v_pk_fma_f32 v[48:49], v[48:49], v[140:141], v[162:163]
	global_store_dwordx4 v[156:157], v[48:51], off
	s_waitcnt vmcnt(11)
	v_pk_fma_f32 v[46:47], v[46:47], v[146:147], v[168:169]
	v_pk_fma_f32 v[44:45], v[44:45], v[144:145], v[166:167]
	global_store_dwordx4 v[156:157], v[44:47], off offset:64
	v_mul_f32_e32 v160, v47, v47
	v_fmac_f32_e32 v160, v46, v46
	s_waitcnt vmcnt(11)
	v_pk_fma_f32 v[42:43], v[42:43], v[138:139], v[172:173]
	v_pk_fma_f32 v[40:41], v[40:41], v[136:137], v[170:171]
	global_store_dwordx4 v[156:157], v[40:43], off offset:512
	v_mul_f32_e32 v158, v49, v49
	v_mul_f32_e32 v159, v51, v51
	v_fmac_f32_e32 v158, v48, v48
	v_fmac_f32_e32 v159, v50, v50
	v_add_f32_e32 v158, v158, v159
	v_mul_f32_e32 v159, v45, v45
	v_fmac_f32_e32 v159, v44, v44
	v_add_f32_e32 v159, v159, v160
	v_add_f32_e32 v158, v158, v159
	v_mul_f32_e32 v159, v41, v41
	v_mul_f32_e32 v160, v43, v43
	v_fmac_f32_e32 v159, v40, v40
	v_fmac_f32_e32 v160, v42, v42
	v_add_f32_e32 v159, v159, v160
	v_add_f32_e32 v158, v158, v159
	s_waitcnt vmcnt(11)
	v_pk_fma_f32 v[38:39], v[38:39], v[134:135], v[176:177]
	v_pk_fma_f32 v[36:37], v[36:37], v[132:133], v[174:175]
	v_mul_f32_e32 v153, v39, v39
	v_mul_f32_e32 v152, v37, v37
	v_fmac_f32_e32 v152, v36, v36
	v_fmac_f32_e32 v153, v38, v38
	v_add_f32_e32 v152, v152, v153
	v_add_f32_e32 v152, v158, v152
	ds_bpermute_b32 v153, v150, v152
	global_store_dwordx4 v[156:157], v[36:39], off offset:576
	s_waitcnt lgkmcnt(0)
	v_add_f32_e32 v152, v152, v153
	ds_bpermute_b32 v153, v151, v152
	s_and_saveexec_b64 s[30:31], vcc
	s_cbranch_execz .LBB0_627
	s_waitcnt lgkmcnt(0)
	v_add_f32_e32 v152, v152, v153
	ds_write_b32 v148, v152 offset:2304
;     __device__ __forceinline__ void fused(f32x4 (&acc)[2][2][4][2], const Unit& u, int wr, int wc, int fr, int fq, PG8_LAS unsigned char* lds, int wid, int lane) const {
;     ...
;             for (int m = 0; m < 4; ++m) { const size_t ro = (size_t)(row0 + ai * HALF + m * 16) * 1024 + col0; float s = 0.f;
; #pragma unroll
;                 for (int bj = 0; bj < 2; ++bj)
; #pragma unroll
;                     for (int n = 0; n < 2; ++n) { const f32x4 xi = __builtin_nontemporal_load((const f32x4*)(xin + ro + bj * HALF + 16 * n));
;                         const f32x4 v = xi + gt[bj][n] * acc[ai][bj][m][n]; acc[ai][bj][m][n] = v;
;                         *(f32x4*)(xout + ro + bj * HALF + 16 * n) = v;
;                         s += (v[0] * v[0] + v[1] * v[1]) + (v[2] * v[2] + v[3] * v[3]); }
;                 s += __shfl_xor(s, 16); s += __shfl_xor(s, 32);
;                 if (fq == 0) P[(ai * HALF + wr * 64 + m * 16 + fr) * 4 + wc] = s; }
.LBB0_627:
	s_or_b64 exec, exec, s[30:31]
	v_add_u32_e32 v204, 0xa0, v182
	v_ashrrev_i32_e32 v205, 31, v204
	s_waitcnt lgkmcnt(0)
	v_lshlrev_b64 v[152:153], 10, v[204:205]
	v_lshl_add_u64 v[152:153], v[152:153], 0, v[180:181]
	v_lshlrev_b64 v[156:157], 2, v[152:153]
	v_lshl_add_u64 v[158:159], s[18:19], 0, v[156:157]
	s_mov_b64 s[98:99], 0xb0000
	v_lshl_add_u64 v[178:179], v[194:195], 0, s[98:99]
	global_load_dwordx4 v[162:165], v[178:179], off nt
	global_load_dwordx4 v[166:169], v[178:179], off offset:64 nt
	global_load_dwordx4 v[170:173], v[178:179], off offset:512 nt
	global_load_dwordx4 v[174:177], v[178:179], off offset:576 nt
	v_lshl_add_u64 v[156:157], s[78:79], 0, v[156:157]
	s_waitcnt vmcnt(11)
	v_pk_fma_f32 v[34:35], v[34:35], v[142:143], v[214:215]
	v_pk_fma_f32 v[32:33], v[32:33], v[140:141], v[212:213]
	global_store_dwordx4 v[156:157], v[32:35], off
	s_waitcnt vmcnt(11)
	v_pk_fma_f32 v[30:31], v[30:31], v[146:147], v[218:219]
	v_pk_fma_f32 v[28:29], v[28:29], v[144:145], v[216:217]
	global_store_dwordx4 v[156:157], v[28:31], off offset:64
	v_mul_f32_e32 v160, v31, v31
	v_fmac_f32_e32 v160, v30, v30
	s_waitcnt vmcnt(11)
	v_pk_fma_f32 v[26:27], v[26:27], v[138:139], v[222:223]
	v_pk_fma_f32 v[24:25], v[24:25], v[136:137], v[220:221]
	global_store_dwordx4 v[156:157], v[24:27], off offset:512
	v_mul_f32_e32 v158, v33, v33
	v_mul_f32_e32 v159, v35, v35
	v_fmac_f32_e32 v158, v32, v32
	v_fmac_f32_e32 v159, v34, v34
	v_add_f32_e32 v158, v158, v159
	v_mul_f32_e32 v159, v29, v29
	v_fmac_f32_e32 v159, v28, v28
	v_add_f32_e32 v159, v159, v160
	v_add_f32_e32 v158, v158, v159
	v_mul_f32_e32 v159, v25, v25
	v_mul_f32_e32 v160, v27, v27
	v_fmac_f32_e32 v159, v24, v24
	v_fmac_f32_e32 v160, v26, v26
	v_add_f32_e32 v159, v159, v160
	v_add_f32_e32 v158, v158, v159
	s_waitcnt vmcnt(11)
	v_pk_fma_f32 v[22:23], v[22:23], v[134:135], v[244:245]
	v_pk_fma_f32 v[20:21], v[20:21], v[132:133], v[242:243]
	v_mul_f32_e32 v153, v23, v23
	v_mul_f32_e32 v152, v21, v21
	v_fmac_f32_e32 v152, v20, v20
	v_fmac_f32_e32 v153, v22, v22
	v_add_f32_e32 v152, v152, v153
	v_add_f32_e32 v152, v158, v152
	ds_bpermute_b32 v153, v150, v152
	global_store_dwordx4 v[156:157], v[20:23], off offset:576
	s_waitcnt lgkmcnt(0)
	v_add_f32_e32 v152, v152, v153
	ds_bpermute_b32 v153, v151, v152
	s_and_saveexec_b64 s[30:31], vcc
	s_cbranch_execz .LBB0_629
	s_waitcnt lgkmcnt(0)
	v_add_f32_e32 v152, v152, v153
	ds_write_b32 v148, v152 offset:2560
.LBB0_629:
	s_or_b64 exec, exec, s[30:31]
	v_add_u32_e32 v206, 0xb0, v182
	v_ashrrev_i32_e32 v207, 31, v206
	s_waitcnt lgkmcnt(0)
	v_lshlrev_b64 v[152:153], 10, v[206:207]
	v_lshl_add_u64 v[152:153], v[152:153], 0, v[180:181]
	v_lshlrev_b64 v[156:157], 2, v[152:153]
	v_lshl_add_u64 v[158:159], s[18:19], 0, v[156:157]
	v_lshl_add_u64 v[156:157], s[78:79], 0, v[156:157]
	s_waitcnt vmcnt(7)
	v_pk_fma_f32 v[18:19], v[18:19], v[142:143], v[164:165]
	v_pk_fma_f32 v[16:17], v[16:17], v[140:141], v[162:163]
	global_store_dwordx4 v[156:157], v[16:19], off
	s_waitcnt vmcnt(7)
	v_pk_fma_f32 v[14:15], v[14:15], v[146:147], v[168:169]
	v_pk_fma_f32 v[12:13], v[12:13], v[144:145], v[166:167]
	global_store_dwordx4 v[156:157], v[12:15], off offset:64
	s_waitcnt vmcnt(7)
	v_pk_fma_f32 v[10:11], v[10:11], v[138:139], v[172:173]
	v_pk_fma_f32 v[8:9], v[8:9], v[136:137], v[170:171]
	global_store_dwordx4 v[156:157], v[8:11], off offset:512
	v_mul_f32_e32 v140, v17, v17
	v_mul_f32_e32 v141, v19, v19
	v_fmac_f32_e32 v140, v16, v16
	v_fmac_f32_e32 v141, v18, v18
	v_add_f32_e32 v140, v140, v141
	v_mul_f32_e32 v141, v13, v13
	v_mul_f32_e32 v142, v15, v15
	v_fmac_f32_e32 v141, v12, v12
	v_fmac_f32_e32 v142, v14, v14
	v_add_f32_e32 v141, v141, v142
	v_add_f32_e32 v140, v140, v141
	v_mul_f32_e32 v141, v9, v9
	v_mul_f32_e32 v142, v11, v11
	v_fmac_f32_e32 v141, v8, v8
	v_fmac_f32_e32 v142, v10, v10
	v_add_f32_e32 v141, v141, v142
	v_add_f32_e32 v140, v140, v141
	s_waitcnt vmcnt(7)
	v_pk_fma_f32 v[6:7], v[6:7], v[134:135], v[176:177]
	v_pk_fma_f32 v[4:5], v[4:5], v[132:133], v[174:175]
	v_mul_f32_e32 v133, v7, v7
	v_mul_f32_e32 v132, v5, v5
	v_fmac_f32_e32 v132, v4, v4
	v_fmac_f32_e32 v133, v6, v6
	v_add_f32_e32 v132, v132, v133
	v_add_f32_e32 v132, v140, v132
	ds_bpermute_b32 v133, v150, v132
	global_store_dwordx4 v[156:157], v[4:7], off offset:576
	s_waitcnt lgkmcnt(0)
	v_add_f32_e32 v132, v132, v133
	ds_bpermute_b32 v133, v151, v132
	s_and_saveexec_b64 s[30:31], vcc
	s_cbranch_execz .LBB0_631
	s_waitcnt lgkmcnt(0)
	v_add_f32_e32 v132, v132, v133
	ds_write_b32 v148, v132 offset:2816
